# strategy 9 loop-edge: attention steady loop back-edge rotation - ring/counter SALU and exit test hoisted above the step barriers, exit path gets its own barrier copy
# baseline (speedup 1.0000x reference)
.Lrot_body:
	v_add_u32_e32 v0, s20, v251
	ds_read_b64_tr_b16 v[208:209], v0 offset:24576
	ds_read_b64_tr_b16 v[210:211], v0 offset:25088
	s_waitcnt lgkmcnt(9)
	v_mfma_f32_32x32x16_bf16 v[128:143], v[204:207], v[172:175], v[226:241]
	v_add_f32_e32 v2, v96, v97
	v_add_f32_e32 v2, v98, v2
	v_add_f32_e32 v2, v99, v2
	v_add_f32_e32 v2, v100, v2
	v_add_f32_e32 v2, v101, v2
	v_cvt_pk_bf16_f32 v160, v96, v97
	v_cvt_pk_bf16_f32 v161, v98, v99
	ds_read_b64_tr_b16 v[204:205], v0 offset:28672
	ds_read_b64_tr_b16 v[206:207], v0 offset:29184
	s_waitcnt lgkmcnt(10)
	v_mfma_f32_32x32x16_bf16 v[112:127], v[196:199], v[172:175], v[226:241]
	v_add_f32_e32 v2, v102, v2
	v_add_f32_e32 v2, v103, v2
	v_add_f32_e32 v2, v104, v2
	v_add_f32_e32 v2, v105, v2
	v_cvt_pk_bf16_f32 v162, v100, v101
	v_cvt_pk_bf16_f32 v163, v102, v103
	ds_read_b64_tr_b16 v[10:11], v0 offset:25600
	ds_read_b64_tr_b16 v[12:13], v0 offset:26112
	s_waitcnt lgkmcnt(11)
	v_mfma_f32_32x32x16_bf16 v[128:143], v[200:203], v[168:171], v[128:143]
	v_add_f32_e32 v2, v106, v2
	v_add_f32_e32 v2, v107, v2
	v_add_f32_e32 v2, v108, v2
	v_add_f32_e32 v2, v109, v2
	v_cvt_pk_bf16_f32 v152, v104, v105
	v_cvt_pk_bf16_f32 v153, v106, v107
	ds_read_b64_tr_b16 v[6:7], v0 offset:29696
	ds_read_b64_tr_b16 v[8:9], v0 offset:30208
	s_waitcnt lgkmcnt(12)
	v_mfma_f32_32x32x16_bf16 v[112:127], v[192:195], v[168:171], v[112:127]
	v_add_f32_e32 v2, v110, v2
	v_add_f32_e32 v2, v111, v2
	v_add_f32_e32 v2, v80, v2
	v_add_f32_e32 v14, v81, v2
	v_cvt_pk_bf16_f32 v154, v108, v109
	v_cvt_pk_bf16_f32 v155, v110, v111
	ds_read_b64_tr_b16 v[2:3], v0 offset:26624
	ds_read_b64_tr_b16 v[4:5], v0 offset:27136
	s_waitcnt lgkmcnt(13)
	v_mfma_f32_32x32x16_bf16 v[128:143], v[188:191], v[164:167], v[128:143]
	v_add_f32_e32 v14, v82, v14
	v_add_f32_e32 v14, v83, v14
	v_add_f32_e32 v14, v84, v14
	v_add_f32_e32 v14, v85, v14
	v_cvt_pk_bf16_f32 v148, v80, v81
	v_cvt_pk_bf16_f32 v149, v82, v83
	ds_read_b64_tr_b16 v[100:101], v0 offset:30720
	ds_read_b64_tr_b16 v[102:103], v0 offset:31232
	s_waitcnt lgkmcnt(14)
	v_mfma_f32_32x32x16_bf16 v[112:127], v[184:187], v[164:167], v[112:127]
	v_add_f32_e32 v14, v86, v14
	v_add_f32_e32 v14, v87, v14
	v_add_f32_e32 v14, v88, v14
	v_add_f32_e32 v14, v89, v14
	v_cvt_pk_bf16_f32 v150, v84, v85
	v_cvt_pk_bf16_f32 v151, v86, v87
	ds_read_b64_tr_b16 v[96:97], v0 offset:27648
	ds_read_b64_tr_b16 v[98:99], v0 offset:28160
	s_waitcnt lgkmcnt(14)
	v_mfma_f32_32x32x16_bf16 v[128:143], v[180:183], v[156:159], v[128:143]
	v_add_f32_e32 v14, v90, v14
	v_add_f32_e32 v14, v91, v14
	v_add_f32_e32 v14, v92, v14
	v_add_f32_e32 v14, v93, v14
	v_cvt_pk_bf16_f32 v144, v88, v89
	v_cvt_pk_bf16_f32 v145, v90, v91
	ds_read_b64_tr_b16 v[88:89], v0 offset:31744
	ds_read_b64_tr_b16 v[90:91], v0 offset:32256
	v_mfma_f32_32x32x16_bf16 v[112:127], v[176:179], v[156:159], v[112:127]
	v_add_f32_e32 v14, v94, v14
	v_add_f32_e32 v14, v95, v14
	v_add_f32_e32 v212, v247, v14
	v_cvt_pk_bf16_f32 v146, v92, v93
	v_cvt_pk_bf16_f32 v147, v94, v95
	s_add_u32 s30, s2, s78
	s_addc_u32 s31, s3, s79
	v_lshl_add_u64 v[80:81], v[220:221], 0, s[30:31]
	s_add_i32 s20, s29, s48


	s_mov_b32 s21, m0
	s_mov_b32 m0, s20
	s_nop 0
	global_load_lds_dwordx4 v[80:81], off
	s_mov_b32 m0, s21
	s_add_u32 s30, s2, 0x40000
	s_addc_u32 s31, s3, 0
	v_lshl_add_u64 v[80:81], v[222:223], 0, s[30:31]
	s_lshl_b32 s20, s27, 1

	s_add_i32 s21, s20, s49
	s_mov_b32 s24, m0
	s_mov_b32 m0, s21
	s_nop 0
	global_load_lds_dwordx4 v[80:81], off
	s_mov_b32 m0, s24
	v_lshl_add_u64 v[80:81], v[224:225], 0, s[30:31]
	s_add_i32 s20, s20, s50
	s_mov_b32 s21, m0
	s_mov_b32 m0, s20
	s_nop 0
	global_load_lds_dwordx4 v[80:81], off
	s_mov_b32 m0, s21
	v_max_f32_e32 v80, v128, v129


	v_max3_f32 v81, v130, v131, v113
	v_max3_f32 v80, v80, v112, v114
	v_max3_f32 v80, v80, v115, v132
	v_max3_f32 v81, v81, v134, v135
	v_max3_f32 v80, v80, v133, v116
	v_max3_f32 v81, v81, v118, v119
	v_max3_f32 v80, v80, v117, v136
	v_max3_f32 v81, v81, v138, v139
	v_max3_f32 v80, v80, v137, v120
	v_max3_f32 v81, v81, v122, v123
	v_max3_f32 v80, v80, v121, v140
	v_max3_f32 v81, v81, v142, v143
	v_max3_f32 v80, v80, v141, v124
	v_max3_f32 v81, v81, v126, v127
	v_max3_f32 v80, v80, v125, v81
	v_mov_b32_e32 v81, v80
	s_nop 1
	v_permlane32_swap_b32_e32 v80, v81
	v_max_f32_e32 v80, v80, v81


	s_mov_b32 s20, 0x41000000
	v_cmp_lt_f32_e32 vcc, s20, v80
	s_cmp_lg_u64 vcc, 0

	s_cselect_b64 s[20:21], -1, 0
	s_cbranch_vccnz .LBB0_1997
.LBB0_1990:
	s_waitcnt lgkmcnt(14)
	v_mfma_f32_32x32x16_bf16 v[64:79], v[160:163], v[208:211], v[64:79]
	v_exp_f32_e32 v128, v128
	v_exp_f32_e32 v129, v129
	ds_read_b64_tr_b16 v[92:93], v0 offset:32768
	ds_read_b64_tr_b16 v[94:95], v0 offset:33280
	s_waitcnt lgkmcnt(14)
	v_mfma_f32_32x32x16_bf16 v[48:63], v[160:163], v[204:207], v[48:63]
	v_exp_f32_e32 v130, v130
	v_exp_f32_e32 v131, v131
	ds_read_b64_tr_b16 v[104:105], v0 offset:36864
	ds_read_b64_tr_b16 v[106:107], v0 offset:37376
	v_add_u32_e32 v196, s27, v250
	ds_read_b128 v[84:87], v196
	ds_read_b128 v[80:83], v196 offset:512
	s_waitcnt lgkmcnt(14)
	v_mfma_f32_32x32x16_bf16 v[64:79], v[152:155], v[10:13], v[64:79]
	v_exp_f32_e32 v132, v132
	v_exp_f32_e32 v133, v133
	ds_read_b64_tr_b16 v[108:109], v0 offset:33792
	ds_read_b64_tr_b16 v[110:111], v0 offset:34304
	ds_read_b128 v[184:187], v196 offset:2048
	ds_read_b128 v[176:179], v196 offset:2560
	v_mfma_f32_32x32x16_bf16 v[48:63], v[152:155], v[6:9], v[48:63]
	v_exp_f32_e32 v134, v134
	v_exp_f32_e32 v135, v135
	ds_read_b64_tr_b16 v[188:189], v0 offset:37888
	ds_read_b64_tr_b16 v[190:191], v0 offset:38400
	ds_read_b128 v[180:183], v196 offset:4096
	ds_read_b128 v[6:9], v196 offset:4608
	s_waitcnt lgkmcnt(14)
	v_mfma_f32_32x32x16_bf16 v[64:79], v[148:151], v[2:5], v[64:79]
	v_exp_f32_e32 v136, v136
	v_exp_f32_e32 v137, v137
	ds_read_b64_tr_b16 v[192:193], v0 offset:34816
	ds_read_b64_tr_b16 v[194:195], v0 offset:35328
	ds_read_b128 v[10:13], v196 offset:6144
	ds_read_b128 v[2:5], v196 offset:6656
	v_mfma_f32_32x32x16_bf16 v[48:63], v[148:151], v[100:103], v[48:63]
	v_exp_f32_e32 v138, v138
	v_exp_f32_e32 v139, v139
	ds_read_b64_tr_b16 v[100:101], v0 offset:38912
	ds_read_b64_tr_b16 v[102:103], v0 offset:39424
	v_mfma_f32_32x32x16_bf16 v[64:79], v[144:147], v[96:99], v[64:79]
	v_exp_f32_e32 v140, v140
	v_exp_f32_e32 v141, v141
	ds_read_b64_tr_b16 v[96:97], v0 offset:35840
	ds_read_b64_tr_b16 v[98:99], v0 offset:36352
	v_mfma_f32_32x32x16_bf16 v[48:63], v[144:147], v[88:91], v[48:63]
	v_exp_f32_e32 v142, v142
	v_exp_f32_e32 v143, v143
	ds_read_b64_tr_b16 v[88:89], v0 offset:39936
	ds_read_b64_tr_b16 v[90:91], v0 offset:40448
	s_waitcnt lgkmcnt(14)
	v_mfma_f32_32x32x16_bf16 v[32:47], v[160:163], v[92:95], v[32:47]
	v_exp_f32_e32 v112, v112
	v_exp_f32_e32 v113, v113
	v_mfma_f32_32x32x16_bf16 v[16:31], v[160:163], v[104:107], v[16:31]
	v_exp_f32_e32 v114, v114
	v_exp_f32_e32 v115, v115
	v_mfma_f32_32x32x16_bf16 v[32:47], v[152:155], v[108:111], v[32:47]
	v_exp_f32_e32 v116, v116
	v_exp_f32_e32 v117, v117
	s_waitcnt lgkmcnt(12)
	v_mfma_f32_32x32x16_bf16 v[16:31], v[152:155], v[188:191], v[16:31]
	v_exp_f32_e32 v118, v118
	v_exp_f32_e32 v119, v119
	s_waitcnt lgkmcnt(8)
	v_mfma_f32_32x32x16_bf16 v[32:47], v[148:151], v[192:195], v[32:47]
	v_exp_f32_e32 v120, v120
	v_exp_f32_e32 v121, v121
	s_waitcnt lgkmcnt(4)
	v_mfma_f32_32x32x16_bf16 v[16:31], v[148:151], v[100:103], v[16:31]
	v_exp_f32_e32 v122, v122
	v_exp_f32_e32 v123, v123
	s_waitcnt lgkmcnt(2)
	v_mfma_f32_32x32x16_bf16 v[32:47], v[144:147], v[96:99], v[32:47]
	v_exp_f32_e32 v124, v124
	v_exp_f32_e32 v125, v125
	s_waitcnt lgkmcnt(0)
	v_mfma_f32_32x32x16_bf16 v[16:31], v[144:147], v[88:91], v[16:31]
	v_exp_f32_e32 v126, v126
	v_exp_f32_e32 v127, v127
	s_add_i32 s24, s27, 0x2000
	s_cmpk_lg_i32 s27, 0x4000
	s_cselect_b32 s52, s24, 0
	s_lshl_b32 s24, s29, 1
	s_waitcnt vmcnt(3) lgkmcnt(0)
	s_barrier
	s_andn2_b64 vcc, exec, s[20:21]
	v_add_u32_e32 v0, s46, v252
	s_cbranch_vccnz .LBB0_1992
	s_waitcnt lgkmcnt(0)
	ds_read_b128 v[88:91], v0 offset:96
	ds_read_b128 v[92:95], v0 offset:64
	ds_read_b128 v[96:99], v0 offset:32
	ds_read_b128 v[100:103], v0
	s_waitcnt lgkmcnt(3)
	v_pk_mul_f32 v[76:77], v[76:77], v[88:89]
	s_waitcnt lgkmcnt(2)
	v_pk_mul_f32 v[72:73], v[72:73], v[92:93]
	s_waitcnt lgkmcnt(1)
	v_pk_mul_f32 v[68:69], v[68:69], v[96:97]
	v_pk_mul_f32 v[78:79], v[78:79], v[90:91]
	v_pk_mul_f32 v[74:75], v[74:75], v[94:95]
	v_pk_mul_f32 v[70:71], v[70:71], v[98:99]
	s_waitcnt lgkmcnt(0)
	v_pk_mul_f32 v[66:67], v[66:67], v[102:103]
	v_pk_mul_f32 v[64:65], v[64:65], v[100:101]
	v_pk_mul_f32 v[60:61], v[60:61], v[88:89]
	v_pk_mul_f32 v[56:57], v[56:57], v[92:93]
	v_pk_mul_f32 v[52:53], v[52:53], v[96:97]
	v_pk_mul_f32 v[62:63], v[62:63], v[90:91]
	v_pk_mul_f32 v[58:59], v[58:59], v[94:95]
	v_pk_mul_f32 v[54:55], v[54:55], v[98:99]
	v_pk_mul_f32 v[50:51], v[50:51], v[102:103]
	v_pk_mul_f32 v[48:49], v[48:49], v[100:101]
	v_pk_mul_f32 v[44:45], v[44:45], v[88:89]
	v_pk_mul_f32 v[40:41], v[40:41], v[92:93]
	v_pk_mul_f32 v[36:37], v[36:37], v[96:97]
	v_pk_mul_f32 v[46:47], v[46:47], v[90:91]
	v_pk_mul_f32 v[42:43], v[42:43], v[94:95]
	v_pk_mul_f32 v[38:39], v[38:39], v[98:99]
	v_pk_mul_f32 v[34:35], v[34:35], v[102:103]
	v_pk_mul_f32 v[32:33], v[32:33], v[100:101]
	v_pk_mul_f32 v[28:29], v[28:29], v[88:89]
	v_pk_mul_f32 v[24:25], v[24:25], v[92:93]
	v_pk_mul_f32 v[20:21], v[20:21], v[96:97]
	v_pk_mul_f32 v[30:31], v[30:31], v[90:91]
	v_pk_mul_f32 v[26:27], v[26:27], v[94:95]
	v_pk_mul_f32 v[22:23], v[22:23], v[98:99]
	v_pk_mul_f32 v[18:19], v[18:19], v[102:103]
	v_pk_mul_f32 v[16:17], v[16:17], v[100:101]
.LBB0_1992:


	v_add_u32_e32 v208, s24, v251
	ds_read_b64_tr_b16 v[196:197], v208 offset:24576
	ds_read_b64_tr_b16 v[198:199], v208 offset:25088
	v_mfma_f32_32x32x16_bf16 v[96:111], v[84:87], v[172:175], v[226:241]
	v_add_f32_e32 v88, v128, v129
	v_add_f32_e32 v88, v130, v88
	v_add_f32_e32 v88, v131, v88
	v_add_f32_e32 v88, v132, v88
	v_add_f32_e32 v88, v133, v88
	v_cvt_pk_bf16_f32 v160, v128, v129
	v_cvt_pk_bf16_f32 v161, v130, v131
	ds_read_b64_tr_b16 v[192:193], v208 offset:28672
	ds_read_b64_tr_b16 v[194:195], v208 offset:29184
	v_add_f32_e32 v84, v134, v88
	v_add_f32_e32 v84, v135, v84
	v_add_f32_e32 v84, v136, v84
	v_add_f32_e32 v128, v137, v84
	v_mfma_f32_32x32x16_bf16 v[80:95], v[80:83], v[172:175], v[226:241]
	v_cvt_pk_bf16_f32 v162, v132, v133
	v_cvt_pk_bf16_f32 v163, v134, v135
	ds_read_b64_tr_b16 v[188:189], v208 offset:25600
	ds_read_b64_tr_b16 v[190:191], v208 offset:26112
	v_mfma_f32_32x32x16_bf16 v[96:111], v[184:187], v[168:171], v[96:111]
	v_add_f32_e32 v128, v138, v128
	v_add_f32_e32 v128, v139, v128
	v_add_f32_e32 v128, v140, v128
	v_add_f32_e32 v128, v141, v128
	v_cvt_pk_bf16_f32 v152, v136, v137
	v_cvt_pk_bf16_f32 v153, v138, v139
	ds_read_b64_tr_b16 v[136:137], v208 offset:29696
	ds_read_b64_tr_b16 v[138:139], v208 offset:30208
	v_mfma_f32_32x32x16_bf16 v[80:95], v[176:179], v[168:171], v[80:95]
	v_add_f32_e32 v128, v142, v128
	v_add_f32_e32 v128, v143, v128
	v_add_f32_e32 v128, v112, v128
	v_add_f32_e32 v128, v113, v128
	v_cvt_pk_bf16_f32 v154, v140, v141
	v_cvt_pk_bf16_f32 v155, v142, v143
	ds_read_b64_tr_b16 v[132:133], v208 offset:26624
	ds_read_b64_tr_b16 v[134:135], v208 offset:27136
	v_mfma_f32_32x32x16_bf16 v[96:111], v[180:183], v[164:167], v[96:111]
	v_add_f32_e32 v128, v114, v128
	v_add_f32_e32 v128, v115, v128
	v_add_f32_e32 v128, v116, v128
	v_add_f32_e32 v140, v117, v128
	v_cvt_pk_bf16_f32 v148, v112, v113
	v_cvt_pk_bf16_f32 v149, v114, v115
	ds_read_b64_tr_b16 v[128:129], v208 offset:30720
	ds_read_b64_tr_b16 v[130:131], v208 offset:31232
	v_mfma_f32_32x32x16_bf16 v[80:95], v[6:9], v[164:167], v[80:95]
	v_add_f32_e32 v6, v118, v140
	v_add_f32_e32 v6, v119, v6
	v_add_f32_e32 v6, v120, v6
	v_add_f32_e32 v6, v121, v6
	v_cvt_pk_bf16_f32 v150, v116, v117
	v_cvt_pk_bf16_f32 v151, v118, v119
	ds_read_b64_tr_b16 v[112:113], v208 offset:27648
	ds_read_b64_tr_b16 v[114:115], v208 offset:28160
	v_mfma_f32_32x32x16_bf16 v[96:111], v[10:13], v[156:159], v[96:111]
	v_add_f32_e32 v6, v122, v6
	v_add_f32_e32 v6, v123, v6
	v_add_f32_e32 v6, v124, v6
	v_add_f32_e32 v10, v125, v6
	v_cvt_pk_bf16_f32 v144, v120, v121
	v_cvt_pk_bf16_f32 v145, v122, v123
	ds_read_b64_tr_b16 v[6:7], v208 offset:31744
	ds_read_b64_tr_b16 v[8:9], v208 offset:32256
	v_mfma_f32_32x32x16_bf16 v[80:95], v[2:5], v[156:159], v[80:95]
	v_add_f32_e32 v2, v126, v10
	v_add_f32_e32 v2, v127, v2
	v_add_f32_e32 v247, v212, v2
	v_cvt_pk_bf16_f32 v146, v124, v125
	v_cvt_pk_bf16_f32 v147, v126, v127
	s_add_u32 s20, s2, 0xa0000
	s_addc_u32 s21, s3, 0
	v_lshl_add_u64 v[2:3], v[220:221], 0, s[20:21]
	s_add_i32 s20, s27, s48
	s_mov_b32 s21, m0
	s_mov_b32 m0, s20
	s_nop 0
	global_load_lds_dwordx4 v[2:3], off
	s_mov_b32 m0, s21
	s_add_u32 s30, s2, s56
	s_addc_u32 s31, s3, s57
	v_lshl_add_u64 v[2:3], v[222:223], 0, s[30:31]
	s_lshl_b32 s20, s52, 1
	s_add_i32 s21, s20, s49
	s_mov_b32 s24, m0
	s_mov_b32 m0, s21
	s_nop 0
	global_load_lds_dwordx4 v[2:3], off
	s_mov_b32 m0, s24
	v_lshl_add_u64 v[2:3], v[224:225], 0, s[30:31]
	s_add_i32 s20, s20, s50
	s_mov_b32 s21, m0
	s_mov_b32 m0, s20
	s_nop 0
	global_load_lds_dwordx4 v[2:3], off
	s_mov_b32 m0, s21
	v_max_f32_e32 v2, v96, v97


	v_max3_f32 v3, v98, v99, v81
	v_max3_f32 v2, v2, v80, v82
	v_max3_f32 v2, v2, v83, v100
	v_max3_f32 v3, v3, v102, v103
	v_max3_f32 v2, v2, v101, v84
	v_max3_f32 v3, v3, v86, v87
	v_max3_f32 v2, v2, v85, v104
	v_max3_f32 v3, v3, v106, v107
	v_max3_f32 v2, v2, v105, v88
	v_max3_f32 v3, v3, v90, v91
	v_max3_f32 v2, v2, v89, v108
	v_max3_f32 v3, v3, v110, v111
	v_max3_f32 v2, v2, v109, v92
	v_max3_f32 v3, v3, v94, v95
	v_max3_f32 v2, v2, v93, v3
	v_mov_b32_e32 v3, v2
	s_nop 1
	v_permlane32_swap_b32_e32 v2, v3
	v_max_f32_e32 v2, v2, v3


	s_mov_b32 s20, 0x41000000
	v_cmp_lt_f32_e32 vcc, s20, v2
	s_cmp_lg_u64 vcc, 0

	s_cselect_b64 s[20:21], -1, 0
	s_cbranch_vccnz .LBB0_2000
.LBB0_1993:
	s_waitcnt lgkmcnt(14)
	v_mfma_f32_32x32x16_bf16 v[64:79], v[160:163], v[196:199], v[64:79]
	v_exp_f32_e32 v96, v96
	v_exp_f32_e32 v97, v97
	ds_read_b64_tr_b16 v[2:3], v208 offset:32768
	ds_read_b64_tr_b16 v[4:5], v208 offset:33280
	s_waitcnt lgkmcnt(14)
	v_mfma_f32_32x32x16_bf16 v[48:63], v[160:163], v[192:195], v[48:63]
	v_exp_f32_e32 v98, v98
	v_exp_f32_e32 v99, v99
	ds_read_b64_tr_b16 v[10:11], v208 offset:36864
	ds_read_b64_tr_b16 v[12:13], v208 offset:37376
	v_add_u32_e32 v14, s52, v250
	ds_read_b128 v[204:207], v14
	ds_read_b128 v[196:199], v14 offset:512
	s_waitcnt lgkmcnt(14)
	v_mfma_f32_32x32x16_bf16 v[64:79], v[152:155], v[188:191], v[64:79]
	v_exp_f32_e32 v100, v100
	v_exp_f32_e32 v101, v101
	ds_read_b64_tr_b16 v[116:117], v208 offset:33792
	ds_read_b64_tr_b16 v[118:119], v208 offset:34304
	ds_read_b128 v[200:203], v14 offset:2048
	ds_read_b128 v[192:195], v14 offset:2560
	v_mfma_f32_32x32x16_bf16 v[48:63], v[152:155], v[136:139], v[48:63]
	v_exp_f32_e32 v102, v102
	v_exp_f32_e32 v103, v103
	ds_read_b64_tr_b16 v[120:121], v208 offset:37888
	ds_read_b64_tr_b16 v[122:123], v208 offset:38400
	ds_read_b128 v[188:191], v14 offset:4096
	ds_read_b128 v[184:187], v14 offset:4608
	s_waitcnt lgkmcnt(14)
	v_mfma_f32_32x32x16_bf16 v[64:79], v[148:151], v[132:135], v[64:79]
	v_exp_f32_e32 v104, v104
	v_exp_f32_e32 v105, v105
	ds_read_b64_tr_b16 v[124:125], v208 offset:34816
	ds_read_b64_tr_b16 v[126:127], v208 offset:35328
	ds_read_b128 v[180:183], v14 offset:6144
	ds_read_b128 v[176:179], v14 offset:6656
	v_mfma_f32_32x32x16_bf16 v[48:63], v[148:151], v[128:131], v[48:63]
	v_exp_f32_e32 v106, v106
	v_exp_f32_e32 v107, v107
	ds_read_b64_tr_b16 v[128:129], v208 offset:38912
	ds_read_b64_tr_b16 v[130:131], v208 offset:39424
	v_mfma_f32_32x32x16_bf16 v[64:79], v[144:147], v[112:115], v[64:79]
	v_exp_f32_e32 v108, v108
	v_exp_f32_e32 v109, v109
	ds_read_b64_tr_b16 v[112:113], v208 offset:35840
	ds_read_b64_tr_b16 v[114:115], v208 offset:36352
	v_mfma_f32_32x32x16_bf16 v[48:63], v[144:147], v[6:9], v[48:63]
	v_exp_f32_e32 v110, v110
	v_exp_f32_e32 v111, v111
	ds_read_b64_tr_b16 v[6:7], v208 offset:39936
	ds_read_b64_tr_b16 v[8:9], v208 offset:40448
	s_waitcnt lgkmcnt(14)
	v_mfma_f32_32x32x16_bf16 v[32:47], v[160:163], v[2:5], v[32:47]
	v_exp_f32_e32 v80, v80
	v_exp_f32_e32 v81, v81
	v_mfma_f32_32x32x16_bf16 v[16:31], v[160:163], v[10:13], v[16:31]
	v_exp_f32_e32 v82, v82
	v_exp_f32_e32 v83, v83
	v_mfma_f32_32x32x16_bf16 v[32:47], v[152:155], v[116:119], v[32:47]
	v_exp_f32_e32 v84, v84
	v_exp_f32_e32 v85, v85
	s_waitcnt lgkmcnt(12)
	v_mfma_f32_32x32x16_bf16 v[16:31], v[152:155], v[120:123], v[16:31]
	v_exp_f32_e32 v86, v86
	v_exp_f32_e32 v87, v87
	s_waitcnt lgkmcnt(8)
	v_mfma_f32_32x32x16_bf16 v[32:47], v[148:151], v[124:127], v[32:47]
	v_exp_f32_e32 v88, v88
	v_exp_f32_e32 v89, v89
	s_waitcnt lgkmcnt(4)
	v_mfma_f32_32x32x16_bf16 v[16:31], v[148:151], v[128:131], v[16:31]
	v_exp_f32_e32 v90, v90
	v_exp_f32_e32 v91, v91
	s_waitcnt lgkmcnt(2)
	v_mfma_f32_32x32x16_bf16 v[32:47], v[144:147], v[112:115], v[32:47]
	v_exp_f32_e32 v92, v92
	v_exp_f32_e32 v93, v93
	s_waitcnt lgkmcnt(0)
	v_mfma_f32_32x32x16_bf16 v[16:31], v[144:147], v[6:9], v[16:31]
	v_exp_f32_e32 v94, v94
	v_exp_f32_e32 v95, v95
	s_add_i32 s24, s52, 0x2000
	s_cmpk_lg_i32 s52, 0x4000
	s_cselect_b32 s54, s24, 0
	s_add_u32 s2, s2, 0x40000
	s_addc_u32 s3, s3, 0
	s_add_i32 s24, s28, 2
	s_cmp_ge_u32 s24, s51
	s_cbranch_scc1 .Lrot_exit
	s_mov_b32 s28, s24
	s_mov_b32 s30, s27
	s_mov_b32 s29, s52
	s_mov_b32 s27, s54
	s_waitcnt vmcnt(3) lgkmcnt(0)
	s_barrier
	s_andn2_b64 vcc, exec, s[20:21]
	s_cbranch_vccnz .LBB0_1995
	s_waitcnt lgkmcnt(0)
	ds_read_b128 v[2:5], v0 offset:96
	ds_read_b128 v[6:9], v0 offset:64
	ds_read_b128 v[10:13], v0 offset:32
	ds_read_b128 v[112:115], v0
	s_waitcnt lgkmcnt(3)
	v_pk_mul_f32 v[76:77], v[76:77], v[2:3]
	s_waitcnt lgkmcnt(2)
	v_pk_mul_f32 v[72:73], v[72:73], v[6:7]
	s_waitcnt lgkmcnt(1)
	v_pk_mul_f32 v[68:69], v[68:69], v[10:11]
	v_pk_mul_f32 v[78:79], v[78:79], v[4:5]
	v_pk_mul_f32 v[74:75], v[74:75], v[8:9]
	v_pk_mul_f32 v[70:71], v[70:71], v[12:13]
	s_waitcnt lgkmcnt(0)
	v_pk_mul_f32 v[66:67], v[66:67], v[114:115]
	v_pk_mul_f32 v[64:65], v[64:65], v[112:113]
	v_pk_mul_f32 v[60:61], v[60:61], v[2:3]
	v_pk_mul_f32 v[56:57], v[56:57], v[6:7]
	v_pk_mul_f32 v[52:53], v[52:53], v[10:11]
	v_pk_mul_f32 v[62:63], v[62:63], v[4:5]
	v_pk_mul_f32 v[58:59], v[58:59], v[8:9]
	v_pk_mul_f32 v[54:55], v[54:55], v[12:13]
	v_pk_mul_f32 v[50:51], v[50:51], v[114:115]
	v_pk_mul_f32 v[48:49], v[48:49], v[112:113]
	v_pk_mul_f32 v[44:45], v[44:45], v[2:3]
	v_pk_mul_f32 v[40:41], v[40:41], v[6:7]
	v_pk_mul_f32 v[36:37], v[36:37], v[10:11]
	v_pk_mul_f32 v[46:47], v[46:47], v[4:5]
	v_pk_mul_f32 v[42:43], v[42:43], v[8:9]
	v_pk_mul_f32 v[38:39], v[38:39], v[12:13]
	v_pk_mul_f32 v[34:35], v[34:35], v[114:115]
	v_pk_mul_f32 v[32:33], v[32:33], v[112:113]
	v_pk_mul_f32 v[28:29], v[28:29], v[2:3]
	v_pk_mul_f32 v[24:25], v[24:25], v[6:7]
	v_pk_mul_f32 v[20:21], v[20:21], v[10:11]
	v_pk_mul_f32 v[30:31], v[30:31], v[4:5]
	v_pk_mul_f32 v[26:27], v[26:27], v[8:9]
	v_pk_mul_f32 v[22:23], v[22:23], v[12:13]
	v_pk_mul_f32 v[18:19], v[18:19], v[114:115]
	v_pk_mul_f32 v[16:17], v[16:17], v[112:113]
.LBB0_1995:
	s_lshl_b32 s20, s30, 1
	s_branch .Lrot_body
.Lrot_exit:
	s_waitcnt vmcnt(3) lgkmcnt(0)
	s_barrier
	s_andn2_b64 vcc, exec, s[20:21]
	s_mov_b32 s20, s24
	s_cbranch_vccnz .Lnegm_exit
	s_waitcnt lgkmcnt(0)
	ds_read_b128 v[2:5], v0 offset:96
	ds_read_b128 v[6:9], v0 offset:64
	ds_read_b128 v[10:13], v0 offset:32
	ds_read_b128 v[112:115], v0
	s_waitcnt lgkmcnt(3)
	v_pk_mul_f32 v[76:77], v[76:77], v[2:3]
	s_waitcnt lgkmcnt(2)
	v_pk_mul_f32 v[72:73], v[72:73], v[6:7]
	s_waitcnt lgkmcnt(1)
	v_pk_mul_f32 v[68:69], v[68:69], v[10:11]
	v_pk_mul_f32 v[78:79], v[78:79], v[4:5]
	v_pk_mul_f32 v[74:75], v[74:75], v[8:9]
	v_pk_mul_f32 v[70:71], v[70:71], v[12:13]
	s_waitcnt lgkmcnt(0)
	v_pk_mul_f32 v[66:67], v[66:67], v[114:115]
	v_pk_mul_f32 v[64:65], v[64:65], v[112:113]
	v_pk_mul_f32 v[60:61], v[60:61], v[2:3]
	v_pk_mul_f32 v[56:57], v[56:57], v[6:7]
	v_pk_mul_f32 v[52:53], v[52:53], v[10:11]
	v_pk_mul_f32 v[62:63], v[62:63], v[4:5]
	v_pk_mul_f32 v[58:59], v[58:59], v[8:9]
	v_pk_mul_f32 v[54:55], v[54:55], v[12:13]
	v_pk_mul_f32 v[50:51], v[50:51], v[114:115]
	v_pk_mul_f32 v[48:49], v[48:49], v[112:113]
	v_pk_mul_f32 v[44:45], v[44:45], v[2:3]
	v_pk_mul_f32 v[40:41], v[40:41], v[6:7]
	v_pk_mul_f32 v[36:37], v[36:37], v[10:11]
	v_pk_mul_f32 v[46:47], v[46:47], v[4:5]
	v_pk_mul_f32 v[42:43], v[42:43], v[8:9]
	v_pk_mul_f32 v[38:39], v[38:39], v[12:13]
	v_pk_mul_f32 v[34:35], v[34:35], v[114:115]
	v_pk_mul_f32 v[32:33], v[32:33], v[112:113]
	v_pk_mul_f32 v[28:29], v[28:29], v[2:3]
	v_pk_mul_f32 v[24:25], v[24:25], v[6:7]
	v_pk_mul_f32 v[20:21], v[20:21], v[10:11]
	v_pk_mul_f32 v[30:31], v[30:31], v[4:5]
	v_pk_mul_f32 v[26:27], v[26:27], v[8:9]
	v_pk_mul_f32 v[22:23], v[22:23], v[12:13]
	v_pk_mul_f32 v[18:19], v[18:19], v[114:115]
	v_pk_mul_f32 v[16:17], v[16:17], v[112:113]
	s_branch .Lnegm_exit
